# epilogue reuses the (pm,pn) of the current unit cached from the previous outer iteration instead of recomputing tile_of (8 GEMM phases); remaining zero-init runs use 64-bit moves
# baseline (speedup 1.0000x reference)
; #define PG8_STAGE(bufoff, gbase, voff, p64) do { _Pragma("unroll") for (int _i = 0; _i < 2; ++_i) { \
;         const char* _gb = (const char*)(gbase) + (size_t)_i * (p64); const unsigned _la = ldsbase + (unsigned)(bufoff) + (unsigned)_i * 8192u; \
;         asm volatile("s_mov_b32 m0, %0\n\ts_nop 0\n\tglobal_load_lds_dwordx4 %1, %2" :: "s"(_la), "v"(voff), "s"(_gb) : "memory"); } } while (0)
; #define PG8_WAIT_V(n) asm volatile("s_waitcnt vmcnt(" #n ")" ::: "memory")
; #define PG8_BAR __builtin_amdgcn_s_barrier()
; template <class Epi, class Sched>
; __device__ __forceinline__ void gemm_phase(LAS unsigned char* lds, const Sched& S, const Epi& E) {
;     ...
;     PG8_STAGE(PG8_SB(0, 0), cB, voffB, hB / 2); PG8_STAGE(PG8_SB(0, 1), cB + hB, voffB, hB / 2); PG8_STAGE(PG8_SA(0, 0), cA, voffA, hA / 2); PG8_STAGE(PG8_SA(0, 1), cA + hA, voffA, hA / 2);
;     if (wr == 1) PG8_BAR;
;     PG8_WAIT_V(2); PG8_BAR;
;     PG8_STAGE(PG8_SB(1, 0), cB + kstep, voffB, hB / 2); PG8_STAGE(PG8_SA(1, 0), cA + kstep, voffA, hA / 2); PG8_STAGE(PG8_SB(1, 1), cB + hB + kstep, voffB, hB / 2);
;     PG8_WAIT_V(6); PG8_BAR;
.LBB0_971:
	v_bfe_u32 v161, v0, 4, 2
	s_add_u32 s48, s8, 0x3e00000
	v_and_b32_e32 v160, 15, v0
	v_lshlrev_b32_e32 v1, 4, v161
	v_lshlrev_b32_e32 v0, 2, v0
	s_addc_u32 s49, s9, 0
	v_lshl_or_b32 v1, v160, 6, v1
	s_lshl_b32 s8, s18, 13
	v_and_b32_e32 v0, 32, v0
	v_bitop3_b32 v2, v1, s8, v0 bitop3:0xde
	s_lshl_b32 s8, s15, 5
	s_and_b32 s51, s8, 0x60
	s_lshl_b32 s50, s18, 6
	s_lshl_b32 s8, s51, 7
	v_bitop3_b32 v0, v1, s8, v0 bitop3:0xde
	s_add_u32 s8, s38, 0x80
	s_addc_u32 s9, s39, 0
	s_add_i32 s52, s34, 0x18000
	s_waitcnt vmcnt(2)
	s_barrier
	s_mov_b32 m0, s52
	s_nop 0
	global_load_lds_dwordx4 v159, s[8:9]
	s_add_u32 s8, s38, 0x20080
	s_addc_u32 s9, s39, 0
	s_add_i32 s53, s34, 0x1a000
	s_mov_b32 m0, s53
	s_nop 0
	global_load_lds_dwordx4 v159, s[8:9]
	s_add_u32 s8, s26, 0x80
	s_addc_u32 s9, s27, 0
	s_add_i32 s54, s34, 0x8000
	s_mov_b32 m0, s54
	s_nop 0
	global_load_lds_dwordx4 v158, s[8:9]
	s_add_u32 s8, s26, 0x20080
	s_addc_u32 s9, s27, 0
	s_add_i32 s55, s34, 0xa000
	s_mov_b32 m0, s55
	s_nop 0
	global_load_lds_dwordx4 v158, s[8:9]
	s_add_u32 s8, s38, 0x40080
	s_addc_u32 s9, s39, 0
	s_add_i32 s56, s34, 0x1c000
	s_mov_b32 m0, s56
	s_nop 0
	global_load_lds_dwordx4 v159, s[8:9]
	s_add_u32 s8, s38, 0x60080
	s_addc_u32 s9, s39, 0
	s_add_i32 s57, s34, 0x1e000
	s_mov_b32 m0, s57
	s_nop 0
	global_load_lds_dwordx4 v159, s[8:9]
	s_waitcnt vmcnt(6)
	s_add_i32 s58, s34, 0xc000
	s_cmpk_lt_u32 s14, 0x100
	v_add_u32_e32 v0, 0, v0
	s_cselect_b64 s[14:15], -1, 0
	s_add_i32 s59, s34, 0xe000
	v_mov_b64_e32 v[136:137], 0x400
	s_mov_b64 s[18:19], 0x3ff
	v_mov_b64_e32 v[138:139], 0x3ff
	v_add_u32_e32 v162, 0x10000, v0
	v_add_u32_e32 v163, 0x14000, v0
	v_add_u32_e32 v164, 0, v2
	v_add_u32_e32 v165, 0x18000, v0
	v_add_u32_e32 v166, 0x1c000, v0
	s_mov_b64 s[24:25], s[38:39]
	s_mov_b64 s[22:23], s[26:27]
	s_barrier
	s_mov_b32 s99, -1
	s_branch .LBB0_974

; __device__ __forceinline__ bool tile_of(long Lidx, int nM, int nN, int& pm, int& pn) {
;     const int nwg = nM * nN; if (Lidx >= nwg) return false;
;     int wgid = (int)Lidx; { const int q = nwg / NXCD, r = nwg % NXCD, xcd = wgid % NXCD, off = wgid / NXCD; wgid = (xcd < r ? xcd * (q + 1) : r * (q + 1) + (xcd - r) * q) + off; }
; template <class Epi, class Sched>
; __device__ __forceinline__ void gemm_phase(LAS unsigned char* lds, const Sched& S, const Epi& E) {
;     ...
;         const char* nA = cA; const char* nB = cB; int nnt = nt; bool has_next;
;         { Unit nx; has_next = S.next(ui + 1, nx);
;           if (has_next) { nA = nx.A; nB = nx.B; nnt = nx.nt; } }
.LBB0_974:
	s_mov_b32 s100, s98
	s_mov_b32 s101, s99
	s_add_i32 s60, s21, 1
	s_mul_i32 s8, s60, s29
	s_mul_hi_u32 s9, s60, s28
	s_add_i32 s9, s9, s8
	s_mul_i32 s8, s60, s28
	s_add_u32 s40, s8, s2
	s_addc_u32 s41, s9, s3
	v_cmp_gt_i64_e32 vcc, s[40:41], v[138:139]
	v_cmp_lt_i64_e64 s[8:9], s[40:41], v[136:137]
	s_cbranch_vccnz .LBB0_980
	s_ashr_i32 s22, s40, 31
	s_lshr_b32 s22, s22, 29
	s_add_i32 s24, s40, s22
	s_and_b32 s22, s24, -8
	s_sub_i32 s25, s40, s22
	s_cmp_gt_i32 s25, -1
	s_mov_b64 s[22:23], -1
	s_cbranch_scc0 .LBB0_977
	s_lshl_b32 s40, s25, 7
	s_mov_b64 s[22:23], 0

; __device__ __forceinline__ bool tile_of(long Lidx, int nM, int nN, int& pm, int& pn) {
;     ...
;     const int nig = WGM * nN, gid = wgid / nig, fm = gid * WGM, gsz = (nM - fm) < WGM ? (nM - fm) : WGM;
;     pm = fm + ((wgid % nig) % gsz); pn = (wgid % nig) / gsz; return true;
;     __device__ __forceinline__ bool next(int i, Unit& u) const {
;     ...
;         u.A = A + (size_t)pm * 256 * lda2; u.B = B + (size_t)pn * 256 * ldb2; u.lda2 = lda2; u.ldb2 = ldb2; u.nt = nt; u.kind = 0; u.pm = pm; u.pn = pn; u.z = 0; u.w = 0; return true;
.LBB0_979:
	s_ashr_i32 s22, s24, 3
	s_add_i32 s22, s40, s22
	s_ashr_i32 s23, s22, 31
	s_lshr_b32 s23, s23, 26
	s_add_i32 s23, s22, s23
	s_ashr_i32 s24, s23, 6
	s_lshl_b32 s25, s24, 3
	s_sub_i32 s24, 0x80, s25
	s_min_i32 s30, s24, 8
	s_andn2_b32 s23, s23, 63
	s_sub_i32 s22, s22, s23
	s_ashr_i32 s24, s22, 3
	s_mul_i32 s23, s24, s30
	s_sub_i32 s22, s22, s23
	s_add_i32 s22, s25, s22
	s_mov_b32 s98, s22
	s_mov_b32 s99, s24
	s_ashr_i32 s23, s22, 31
	s_lshl_b64 s[22:23], s[22:23], 19
	s_add_u32 s22, s4, s22
	s_addc_u32 s23, s5, s23
	s_ashr_i32 s25, s24, 31
	s_lshl_b64 s[24:25], s[24:25], 19
	s_add_u32 s24, s31, s24
	s_addc_u32 s25, s33, s25

; __device__ __forceinline__ bool tile_of(long Lidx, int nM, int nN, int& pm, int& pn) {
;     const int nwg = nM * nN; if (Lidx >= nwg) return false;
;     int wgid = (int)Lidx; { const int q = nwg / NXCD, r = nwg % NXCD, xcd = wgid % NXCD, off = wgid / NXCD; wgid = (xcd < r ? xcd * (q + 1) : r * (q + 1) + (xcd - r) * q) + off; }
; template <class Epi, class Sched>
; __device__ __forceinline__ void gemm_phase(LAS unsigned char* lds, const Sched& S, const Epi& E) {
;     ...
;         { int efr = fr, efq = fq, eui = ui; asm volatile("" : "+v"(efr), "+v"(efq), "+s"(eui));
;           Unit eu; S.next(eui, eu); keep = E(acc, eu, wr, wc, efr, efq); }
.LBB0_984:
	v_mov_b32_e32 v113, v161
	v_mov_b32_e32 v112, v160
	v_mov_b32_e32 v116, s28
	v_mov_b64_e32 v[114:115], s[2:3]
	s_nop 0
	v_mad_i64_i32 v[114:115], s[26:27], s21, v116, v[114:115]
	v_cmp_lt_i64_e32 vcc, s[18:19], v[114:115]
	v_readfirstlane_b32 s21, v114
	s_cbranch_vccnz .LBB0_990
	s_cmp_lt_i32 s101, 0
	s_cbranch_scc1 .Lcalc_full_1
	s_mov_b32 s20, s100
	s_mov_b32 s61, s101
	s_branch .LBB0_990
.Lcalc_full_1:
	s_ashr_i32 s20, s21, 31
	s_lshr_b32 s20, s20, 29
	s_add_i32 s26, s21, s20
	s_and_b32 s20, s26, -8
	s_sub_i32 s27, s21, s20
	s_cmp_gt_i32 s27, -1
	s_mov_b64 s[20:21], -1
	s_cbranch_scc0 .LBB0_987
	s_lshl_b32 s38, s27, 7
	s_mov_b64 s[20:21], 0

; #define PG8_STAGE(bufoff, gbase, voff, p64) do { _Pragma("unroll") for (int _i = 0; _i < 2; ++_i) { \
;         const char* _gb = (const char*)(gbase) + (size_t)_i * (p64); const unsigned _la = ldsbase + (unsigned)(bufoff) + (unsigned)_i * 8192u; \
;         asm volatile("s_mov_b32 m0, %0\n\ts_nop 0\n\tglobal_load_lds_dwordx4 %1, %2" :: "s"(_la), "v"(voff), "s"(_gb) : "memory"); } } while (0)
; #define PG8_WAIT_V(n) asm volatile("s_waitcnt vmcnt(" #n ")" ::: "memory")
; #define PG8_BAR __builtin_amdgcn_s_barrier()
; template <class Epi, class Sched>
; __device__ __forceinline__ void gemm_phase(LAS unsigned char* lds, const Sched& S, const Epi& E) {
;     ...
;     PG8_STAGE(PG8_SB(0, 0), cB, voffB, hB / 2); PG8_STAGE(PG8_SB(0, 1), cB + hB, voffB, hB / 2); PG8_STAGE(PG8_SA(0, 0), cA, voffA, hA / 2); PG8_STAGE(PG8_SA(0, 1), cA + hA, voffA, hA / 2);
;     if (wr == 1) PG8_BAR;
;     PG8_WAIT_V(2); PG8_BAR;
;     PG8_STAGE(PG8_SB(1, 0), cB + kstep, voffB, hB / 2); PG8_STAGE(PG8_SA(1, 0), cA + kstep, voffA, hA / 2); PG8_STAGE(PG8_SB(1, 1), cB + hB + kstep, voffB, hB / 2);
;     PG8_WAIT_V(6); PG8_BAR;
.LBB0_1001:
	s_add_u32 s48, s10, 0x8900000
	v_bfe_u32 v137, v0, 4, 2
	s_addc_u32 s49, s11, 0
	v_and_b32_e32 v136, 15, v0
	v_lshlrev_b32_e32 v1, 4, v137
	v_lshlrev_b32_e32 v0, 2, v0
	s_lshl_b32 s6, s6, 5
	v_lshl_or_b32 v1, v136, 6, v1
	s_lshl_b32 s10, s15, 13
	v_and_b32_e32 v0, 32, v0
	s_and_b32 s6, s6, 0x60
	s_lshl_b32 s50, s15, 6
	v_bitop3_b32 v2, v1, s10, v0 bitop3:0xde
	s_lshl_b32 s10, s6, 7
	v_bitop3_b32 v0, v1, s10, v0 bitop3:0xde
	s_add_u32 s10, s38, 0x80
	s_addc_u32 s11, s39, 0
	s_add_i32 s51, s34, 0x18000
	s_waitcnt vmcnt(2)
	s_barrier
	s_mov_b32 m0, s51
	s_nop 0
	global_load_lds_dwordx4 v135, s[10:11]
	s_add_u32 s10, s38, 0x20080
	s_addc_u32 s11, s39, 0
	s_add_i32 s52, s34, 0x1a000
	s_mov_b32 m0, s52
	s_nop 0
	global_load_lds_dwordx4 v135, s[10:11]
	s_add_u32 s10, s26, 0x80
	s_addc_u32 s11, s27, 0
	s_add_i32 s53, s34, 0x8000
	s_mov_b32 m0, s53
	s_nop 0
	global_load_lds_dwordx4 v134, s[10:11]
	s_add_u32 s10, s26, 0x20080
	s_addc_u32 s11, s27, 0
	s_add_i32 s54, s34, 0xa000
	s_mov_b32 m0, s54
	s_nop 0
	global_load_lds_dwordx4 v134, s[10:11]
	s_add_u32 s10, s38, 0x40080
	s_addc_u32 s11, s39, 0
	s_add_i32 s55, s34, 0x1c000
	s_mov_b32 m0, s55
	s_nop 0
	global_load_lds_dwordx4 v135, s[10:11]
	s_add_u32 s10, s38, 0x60080
	s_addc_u32 s11, s39, 0
	s_add_i32 s56, s34, 0x1e000
	s_mov_b32 m0, s56
	s_nop 0
	global_load_lds_dwordx4 v135, s[10:11]
	s_waitcnt vmcnt(6)
	s_add_i32 s57, s34, 0xc000
	s_cmpk_lt_u32 s14, 0x100
	v_add_u32_e32 v0, 0, v0
	s_cselect_b64 s[14:15], -1, 0
	s_add_i32 s58, s34, 0xe000
	v_mov_b64_e32 v[128:129], 0x400
	s_mov_b64 s[18:19], 0x3ff
	v_mov_b64_e32 v[130:131], 0x3ff
	v_add_u32_e32 v138, 0x10000, v0
	v_add_u32_e32 v139, 0x14000, v0
	v_add_u32_e32 v140, 0, v2
	v_add_u32_e32 v141, 0x18000, v0
	v_add_u32_e32 v142, 0x1c000, v0
	s_lshl_b32 s6, s6, 1
	s_mov_b32 s21, s7
	s_mov_b64 s[24:25], s[38:39]
	s_mov_b64 s[22:23], s[26:27]
	s_barrier
	s_waitcnt vmcnt(0)
	s_mov_b32 s99, -1
	s_branch .LBB0_1004

; __device__ __forceinline__ bool tile_of(long Lidx, int nM, int nN, int& pm, int& pn) {
;     const int nwg = nM * nN; if (Lidx >= nwg) return false;
;     int wgid = (int)Lidx; { const int q = nwg / NXCD, r = nwg % NXCD, xcd = wgid % NXCD, off = wgid / NXCD; wgid = (xcd < r ? xcd * (q + 1) : r * (q + 1) + (xcd - r) * q) + off; }
; template <class Epi, class Sched>
; __device__ __forceinline__ void gemm_phase(LAS unsigned char* lds, const Sched& S, const Epi& E) {
;     ...
;         const char* nA = cA; const char* nB = cB; int nnt = nt; bool has_next;
;         { Unit nx; has_next = S.next(ui + 1, nx);
;           if (has_next) { nA = nx.A; nB = nx.B; nnt = nx.nt; } }
.LBB0_1004:
	s_mov_b32 s100, s98
	s_mov_b32 s101, s99
	s_add_i32 s59, s21, 1
	s_mul_i32 s10, s59, s29
	s_mul_hi_u32 s11, s59, s28
	s_add_i32 s11, s11, s10
	s_mul_i32 s10, s59, s28
	s_add_u32 s40, s10, s2
	s_addc_u32 s41, s11, s3
	v_cmp_gt_i64_e32 vcc, s[40:41], v[130:131]
	v_cmp_lt_i64_e64 s[10:11], s[40:41], v[128:129]
	s_cbranch_vccnz .LBB0_1010
	s_ashr_i32 s22, s40, 31
	s_lshr_b32 s22, s22, 29
	s_add_i32 s24, s40, s22
	s_and_b32 s22, s24, -8
	s_sub_i32 s25, s40, s22
	s_cmp_gt_i32 s25, -1
	s_mov_b64 s[22:23], -1
	s_cbranch_scc0 .LBB0_1007
	s_lshl_b32 s40, s25, 7
	s_mov_b64 s[22:23], 0

; __device__ __forceinline__ bool tile_of(long Lidx, int nM, int nN, int& pm, int& pn) {
;     const int nwg = nM * nN; if (Lidx >= nwg) return false;
;     int wgid = (int)Lidx; { const int q = nwg / NXCD, r = nwg % NXCD, xcd = wgid % NXCD, off = wgid / NXCD; wgid = (xcd < r ? xcd * (q + 1) : r * (q + 1) + (xcd - r) * q) + off; }
; template <class Epi, class Sched>
; __device__ __forceinline__ void gemm_phase(LAS unsigned char* lds, const Sched& S, const Epi& E) {
;     ...
;         { int efr = fr, efq = fq, eui = ui; asm volatile("" : "+v"(efr), "+v"(efq), "+s"(eui));
;           Unit eu; S.next(eui, eu); keep = E(acc, eu, wr, wc, efr, efq); }
.LBB0_1014:
	v_mov_b32_e32 v133, v137
	v_mov_b32_e32 v132, v136
	v_mov_b32_e32 v143, s28
	v_mov_b64_e32 v[144:145], s[2:3]
	s_nop 0
	v_mad_i64_i32 v[144:145], s[26:27], s21, v143, v[144:145]
	v_cmp_lt_i64_e32 vcc, s[18:19], v[144:145]
	v_readfirstlane_b32 s21, v144
	s_cbranch_vccnz .LBB0_1020
	s_cmp_lt_i32 s101, 0
	s_cbranch_scc1 .Lcalc_full_2
	s_mov_b32 s20, s100
	s_mov_b32 s60, s101
	s_branch .LBB0_1020

; #define PG8_STAGE(bufoff, gbase, voff, p64) do { _Pragma("unroll") for (int _i = 0; _i < 2; ++_i) { \
;         const char* _gb = (const char*)(gbase) + (size_t)_i * (p64); const unsigned _la = ldsbase + (unsigned)(bufoff) + (unsigned)_i * 8192u; \
;         asm volatile("s_mov_b32 m0, %0\n\ts_nop 0\n\tglobal_load_lds_dwordx4 %1, %2" :: "s"(_la), "v"(voff), "s"(_gb) : "memory"); } } while (0)
; #define PG8_WAIT_V(n) asm volatile("s_waitcnt vmcnt(" #n ")" ::: "memory")
; #define PG8_BAR __builtin_amdgcn_s_barrier()
; template <class Epi, class Sched>
; __device__ __forceinline__ void gemm_phase(LAS unsigned char* lds, const Sched& S, const Epi& E) {
;     ...
;     PG8_STAGE(PG8_SB(0, 0), cB, voffB, hB / 2); PG8_STAGE(PG8_SB(0, 1), cB + hB, voffB, hB / 2); PG8_STAGE(PG8_SA(0, 0), cA, voffA, hA / 2); PG8_STAGE(PG8_SA(0, 1), cA + hA, voffA, hA / 2);
;     if (wr == 1) PG8_BAR;
;     PG8_WAIT_V(2); PG8_BAR;
;     PG8_STAGE(PG8_SB(1, 0), cB + kstep, voffB, hB / 2); PG8_STAGE(PG8_SA(1, 0), cA + kstep, voffA, hA / 2); PG8_STAGE(PG8_SB(1, 1), cB + hB + kstep, voffB, hB / 2);
;     PG8_WAIT_V(6); PG8_BAR;
.LBB0_1079:
	s_add_u32 s14, s14, 0x10900000
	s_addc_u32 s15, s15, 0
	v_bfe_u32 v137, v0, 4, 2
	s_lshl_b32 s11, s11, 5
	v_and_b32_e32 v136, 15, v0
	v_lshlrev_b32_e32 v1, 4, v137
	v_lshlrev_b32_e32 v0, 2, v0
	s_and_b32 s49, s11, 0x60
	s_lshl_b32 s48, s18, 6
	v_lshl_or_b32 v1, v136, 6, v1
	s_lshl_b32 s18, s18, 13
	v_and_b32_e32 v0, 32, v0
	s_lshl_b32 s11, s49, 7
	v_bitop3_b32 v2, v1, s18, v0 bitop3:0xde
	s_add_u32 s18, s40, 0x80
	s_addc_u32 s19, s41, 0
	s_add_i32 s50, s31, 0x18000
	s_waitcnt vmcnt(2)
	s_barrier
	s_mov_b32 m0, s50
	s_nop 0
	global_load_lds_dwordx4 v135, s[18:19]
	s_add_u32 s18, s40, 0x40080
	s_addc_u32 s19, s41, 0
	s_add_i32 s51, s31, 0x1a000
	s_mov_b32 m0, s51
	s_nop 0
	global_load_lds_dwordx4 v135, s[18:19]
	s_add_u32 s18, s38, 0x80
	s_addc_u32 s19, s39, 0
	s_add_i32 s52, s31, 0x8000
	s_mov_b32 m0, s52
	s_nop 0
	global_load_lds_dwordx4 v134, s[18:19]
	s_add_u32 s18, s38, 0x40080
	s_addc_u32 s19, s39, 0
	s_add_i32 s53, s31, 0xa000
	s_mov_b32 m0, s53
	s_nop 0
	global_load_lds_dwordx4 v134, s[18:19]
	s_add_u32 s18, s40, 0x80080
	s_addc_u32 s19, s41, 0
	s_add_i32 s54, s31, 0x1c000
	s_mov_b32 m0, s54
	s_nop 0
	global_load_lds_dwordx4 v135, s[18:19]
	s_add_u32 s18, s40, 0xc0080
	s_addc_u32 s19, s41, 0
	s_add_i32 s55, s31, 0x1e000
	s_mov_b32 m0, s55
	s_nop 0
	global_load_lds_dwordx4 v135, s[18:19]
	v_bitop3_b32 v0, v1, s11, v0 bitop3:0xde
	s_waitcnt vmcnt(6)
	s_add_i32 s56, s31, 0xc000
	s_cmpk_lt_u32 s10, 0x100
	v_add_u32_e32 v0, 0, v0
	s_cselect_b64 s[18:19], -1, 0
	s_add_i32 s57, s31, 0xe000
	v_mov_b64_e32 v[128:129], 0x200
	s_mov_b64 s[20:21], 0x1ff
	v_mov_b64_e32 v[130:131], 0x1ff
	v_add_u32_e32 v138, 0x10000, v0
	v_add_u32_e32 v139, 0x14000, v0
	v_add_u32_e32 v140, 0, v2
	v_add_u32_e32 v141, 0x18000, v0
	v_add_u32_e32 v142, 0x1c000, v0
	s_mov_b64 s[26:27], s[40:41]
	s_mov_b64 s[24:25], s[38:39]
	s_barrier
	s_waitcnt vmcnt(0)
	s_mov_b32 s99, -1
	s_branch .LBB0_1082

; __device__ __forceinline__ bool tile_of(long Lidx, int nM, int nN, int& pm, int& pn) {
;     const int nwg = nM * nN; if (Lidx >= nwg) return false;
;     int wgid = (int)Lidx; { const int q = nwg / NXCD, r = nwg % NXCD, xcd = wgid % NXCD, off = wgid / NXCD; wgid = (xcd < r ? xcd * (q + 1) : r * (q + 1) + (xcd - r) * q) + off; }
; template <class Epi, class Sched>
; __device__ __forceinline__ void gemm_phase(LAS unsigned char* lds, const Sched& S, const Epi& E) {
;     ...
;         const char* nA = cA; const char* nB = cB; int nnt = nt; bool has_next;
;         { Unit nx; has_next = S.next(ui + 1, nx);
;           if (has_next) { nA = nx.A; nB = nx.B; nnt = nx.nt; } }
.LBB0_1082:
	s_mov_b32 s100, s98
	s_mov_b32 s101, s99
	s_add_i32 s58, s23, 1
	s_mul_i32 s10, s58, s29
	s_mul_hi_u32 s11, s58, s28
	s_add_i32 s11, s11, s10
	s_mul_i32 s10, s58, s28
	s_add_u32 s42, s10, s2
	s_addc_u32 s43, s11, s3
	v_cmp_gt_i64_e32 vcc, s[42:43], v[130:131]
	v_cmp_lt_i64_e64 s[10:11], s[42:43], v[128:129]
	s_cbranch_vccnz .LBB0_1088
	s_ashr_i32 s24, s42, 31
	s_lshr_b32 s24, s24, 29
	s_add_i32 s26, s42, s24
	s_and_b32 s24, s26, -8
	s_sub_i32 s27, s42, s24
	s_cmp_gt_i32 s27, -1
	s_mov_b64 s[24:25], -1
	s_cbranch_scc0 .LBB0_1085
	s_lshl_b32 s42, s27, 6
	s_mov_b64 s[24:25], 0

; __device__ __forceinline__ bool tile_of(long Lidx, int nM, int nN, int& pm, int& pn) {
;     ...
;     const int nig = WGM * nN, gid = wgid / nig, fm = gid * WGM, gsz = (nM - fm) < WGM ? (nM - fm) : WGM;
;     pm = fm + ((wgid % nig) % gsz); pn = (wgid % nig) / gsz; return true;
;     __device__ __forceinline__ bool next(int i, Unit& u) const {
;     ...
;         u.A = A + (size_t)pm * 256 * lda2; u.B = B + (size_t)pn * 256 * ldb2; u.lda2 = lda2; u.ldb2 = ldb2; u.nt = nt; u.kind = 0; u.pm = pm; u.pn = pn; u.z = 0; u.w = 0; return true;
.LBB0_1087:
	s_ashr_i32 s24, s26, 3
	s_add_i32 s24, s42, s24
	s_ashr_i32 s25, s24, 31
	s_lshr_b32 s25, s25, 27
	s_add_i32 s25, s24, s25
	s_ashr_i32 s26, s25, 5
	s_lshl_b32 s27, s26, 3
	s_sub_i32 s26, 0x80, s27
	s_min_i32 s30, s26, 8
	s_andn2_b32 s25, s25, 31
	s_sub_i32 s24, s24, s25
	s_ashr_i32 s26, s24, 3
	s_mul_i32 s25, s26, s30
	s_sub_i32 s24, s24, s25
	s_add_i32 s24, s27, s24
	s_mov_b32 s98, s24
	s_mov_b32 s99, s26
	s_ashr_i32 s25, s24, 31
	s_lshl_b64 s[24:25], s[24:25], 20
	s_add_u32 s24, s12, s24
	s_addc_u32 s25, s13, s25
	s_ashr_i32 s27, s26, 31
	s_lshl_b64 s[26:27], s[26:27], 20
	s_add_u32 s26, s4, s26
	s_addc_u32 s27, s5, s27

; __device__ __forceinline__ bool tile_of(long Lidx, int nM, int nN, int& pm, int& pn) {
;     const int nwg = nM * nN; if (Lidx >= nwg) return false;
;     int wgid = (int)Lidx; { const int q = nwg / NXCD, r = nwg % NXCD, xcd = wgid % NXCD, off = wgid / NXCD; wgid = (xcd < r ? xcd * (q + 1) : r * (q + 1) + (xcd - r) * q) + off; }
; template <class Epi, class Sched>
; __device__ __forceinline__ void gemm_phase(LAS unsigned char* lds, const Sched& S, const Epi& E) {
;     ...
;         { int efr = fr, efq = fq, eui = ui; asm volatile("" : "+v"(efr), "+v"(efq), "+s"(eui));
;           Unit eu; S.next(eui, eu); keep = E(acc, eu, wr, wc, efr, efq); }
.LBB0_1092:
	v_mov_b32_e32 v133, v137
	v_mov_b32_e32 v132, v136
	v_mov_b32_e32 v143, s28
	v_mov_b64_e32 v[144:145], s[2:3]
	s_nop 0
	v_mad_i64_i32 v[144:145], s[38:39], s23, v143, v[144:145]
	v_cmp_lt_i64_e32 vcc, s[20:21], v[144:145]
	v_readfirstlane_b32 s23, v144
	s_cbranch_vccnz .LBB0_1098
	s_cmp_lt_i32 s101, 0
	s_cbranch_scc1 .Lcalc_full_3
	s_mov_b32 s22, s100
	s_mov_b32 s59, s101
	s_branch .LBB0_1098
.Lcalc_full_3:
	s_ashr_i32 s22, s23, 31
	s_lshr_b32 s22, s22, 29
	s_add_i32 s38, s23, s22
	s_and_b32 s22, s38, -8
	s_sub_i32 s39, s23, s22
	s_cmp_gt_i32 s39, -1
	s_mov_b64 s[22:23], -1
	s_cbranch_scc0 .LBB0_1095
	s_lshl_b32 s40, s39, 6
	s_mov_b64 s[22:23], 0

; #define PG8_STAGE(bufoff, gbase, voff, p64) do { _Pragma("unroll") for (int _i = 0; _i < 2; ++_i) { \
;         const char* _gb = (const char*)(gbase) + (size_t)_i * (p64); const unsigned _la = ldsbase + (unsigned)(bufoff) + (unsigned)_i * 8192u; \
;         asm volatile("s_mov_b32 m0, %0\n\ts_nop 0\n\tglobal_load_lds_dwordx4 %1, %2" :: "s"(_la), "v"(voff), "s"(_gb) : "memory"); } } while (0)
; #define PG8_WAIT_V(n) asm volatile("s_waitcnt vmcnt(" #n ")" ::: "memory")
; #define PG8_BAR __builtin_amdgcn_s_barrier()
; template <class Epi, class Sched>
; __device__ __forceinline__ void gemm_phase(LAS unsigned char* lds, const Sched& S, const Epi& E) {
;     ...
;     PG8_STAGE(PG8_SB(0, 0), cB, voffB, hB / 2); PG8_STAGE(PG8_SB(0, 1), cB + hB, voffB, hB / 2); PG8_STAGE(PG8_SA(0, 0), cA, voffA, hA / 2); PG8_STAGE(PG8_SA(0, 1), cA + hA, voffA, hA / 2);
;     if (wr == 1) PG8_BAR;
;     PG8_WAIT_V(2); PG8_BAR;
;     PG8_STAGE(PG8_SB(1, 0), cB + kstep, voffB, hB / 2); PG8_STAGE(PG8_SA(1, 0), cA + kstep, voffA, hA / 2); PG8_STAGE(PG8_SB(1, 1), cB + hB + kstep, voffB, hB / 2);
;     PG8_WAIT_V(6); PG8_BAR;
.LBB0_1182:
	v_bfe_u32 v137, v0, 4, 2
	s_add_u32 s12, s10, 0x8900000
	v_and_b32_e32 v136, 15, v0
	v_lshlrev_b32_e32 v1, 4, v137
	v_lshlrev_b32_e32 v0, 2, v0
	s_addc_u32 s13, s11, 0
	v_lshl_or_b32 v1, v136, 6, v1
	s_lshl_b32 s10, s16, 13
	v_and_b32_e32 v0, 32, v0
	v_bitop3_b32 v2, v1, s10, v0 bitop3:0xde
	s_lshl_b32 s10, s15, 5
	s_and_b32 s47, s10, 0x60
	s_lshl_b32 s46, s16, 6
	s_lshl_b32 s10, s47, 7
	v_bitop3_b32 v0, v1, s10, v0 bitop3:0xde
	s_add_u32 s10, s26, 0x80
	s_addc_u32 s11, s27, 0
	s_add_i32 s48, s34, 0x18000
	s_waitcnt vmcnt(2)
	s_barrier
	s_mov_b32 m0, s48
	s_nop 0
	global_load_lds_dwordx4 v135, s[10:11]
	s_add_u32 s10, s26, 0x20080
	s_addc_u32 s11, s27, 0
	s_add_i32 s49, s34, 0x1a000
	s_mov_b32 m0, s49
	s_nop 0
	global_load_lds_dwordx4 v135, s[10:11]
	s_add_u32 s10, s24, 0x80
	s_addc_u32 s11, s25, 0
	s_add_i32 s50, s34, 0x8000
	s_mov_b32 m0, s50
	s_nop 0
	global_load_lds_dwordx4 v134, s[10:11]
	s_add_u32 s10, s24, 0x20080
	s_addc_u32 s11, s25, 0
	s_add_i32 s51, s34, 0xa000
	s_mov_b32 m0, s51
	s_nop 0
	global_load_lds_dwordx4 v134, s[10:11]
	s_add_u32 s10, s26, 0x40080
	s_addc_u32 s11, s27, 0
	s_add_i32 s52, s34, 0x1c000
	s_mov_b32 m0, s52
	s_nop 0
	global_load_lds_dwordx4 v135, s[10:11]
	s_add_u32 s10, s26, 0x60080
	s_addc_u32 s11, s27, 0
	s_add_i32 s53, s34, 0x1e000
	s_mov_b32 m0, s53
	s_nop 0
	global_load_lds_dwordx4 v135, s[10:11]
	s_waitcnt vmcnt(6)
	s_add_i32 s54, s34, 0xc000
	s_cmpk_lt_u32 s14, 0x100
	v_add_u32_e32 v0, 0, v0
	s_cselect_b64 s[14:15], -1, 0
	s_add_i32 s55, s34, 0xe000
	v_mov_b64_e32 v[128:129], 0x200
	s_mov_b64 s[16:17], 0x1ff
	v_mov_b64_e32 v[130:131], 0x1ff
	v_add_u32_e32 v138, 0x10000, v0
	v_add_u32_e32 v139, 0x14000, v0
	v_add_u32_e32 v140, 0, v2
	v_add_u32_e32 v141, 0x18000, v0
	v_add_u32_e32 v142, 0x1c000, v0
	s_mov_b64 s[22:23], s[26:27]
	s_mov_b64 s[20:21], s[24:25]
	s_barrier
	s_waitcnt vmcnt(0)
	s_mov_b32 s99, -1
	s_branch .LBB0_1185

; __device__ __forceinline__ bool tile_of(long Lidx, int nM, int nN, int& pm, int& pn) {
;     const int nwg = nM * nN; if (Lidx >= nwg) return false;
;     int wgid = (int)Lidx; { const int q = nwg / NXCD, r = nwg % NXCD, xcd = wgid % NXCD, off = wgid / NXCD; wgid = (xcd < r ? xcd * (q + 1) : r * (q + 1) + (xcd - r) * q) + off; }
; template <class Epi, class Sched>
; __device__ __forceinline__ void gemm_phase(LAS unsigned char* lds, const Sched& S, const Epi& E) {
;     ...
;         const char* nA = cA; const char* nB = cB; int nnt = nt; bool has_next;
;         { Unit nx; has_next = S.next(ui + 1, nx);
;           if (has_next) { nA = nx.A; nB = nx.B; nnt = nx.nt; } }
.LBB0_1185:
	s_mov_b32 s100, s98
	s_mov_b32 s101, s99
	s_add_i32 s56, s19, 1
	s_mul_i32 s10, s56, s29
	s_mul_hi_u32 s11, s56, s28
	s_add_i32 s11, s11, s10
	s_mul_i32 s10, s56, s28
	s_add_u32 s38, s10, s2
	s_addc_u32 s39, s11, s3
	v_cmp_gt_i64_e32 vcc, s[38:39], v[130:131]
	v_cmp_lt_i64_e64 s[10:11], s[38:39], v[128:129]
	s_cbranch_vccnz .LBB0_1191
	s_ashr_i32 s20, s38, 31
	s_lshr_b32 s20, s20, 29
	s_add_i32 s22, s38, s20
	s_and_b32 s20, s22, -8
	s_sub_i32 s23, s38, s20
	s_cmp_gt_i32 s23, -1
	s_mov_b64 s[20:21], -1
	s_cbranch_scc0 .LBB0_1188
	s_lshl_b32 s38, s23, 6
	s_mov_b64 s[20:21], 0

; __device__ __forceinline__ bool tile_of(long Lidx, int nM, int nN, int& pm, int& pn) {
;     ...
;     const int nig = WGM * nN, gid = wgid / nig, fm = gid * WGM, gsz = (nM - fm) < WGM ? (nM - fm) : WGM;
;     pm = fm + ((wgid % nig) % gsz); pn = (wgid % nig) / gsz; return true;
;     __device__ __forceinline__ bool next(int i, Unit& u) const {
;     ...
;         u.A = A + (size_t)pm * 256 * lda2; u.B = B + (size_t)pn * 256 * ldb2; u.lda2 = lda2; u.ldb2 = ldb2; u.nt = nt; u.kind = 0; u.pm = pm; u.pn = pn; u.z = 0; u.w = 0; return true;
.LBB0_1190:
	s_ashr_i32 s20, s22, 3
	s_add_i32 s20, s38, s20
	s_ashr_i32 s21, s20, 31
	s_lshr_b32 s21, s21, 27
	s_add_i32 s21, s20, s21
	s_ashr_i32 s22, s21, 5
	s_lshl_b32 s23, s22, 3
	s_sub_i32 s22, 0x80, s23
	s_min_i32 s30, s22, 8
	s_andn2_b32 s21, s21, 31
	s_sub_i32 s20, s20, s21
	s_ashr_i32 s22, s20, 3
	s_mul_i32 s21, s22, s30
	s_sub_i32 s20, s20, s21
	s_add_i32 s20, s23, s20
	s_mov_b32 s98, s20
	s_mov_b32 s99, s22
	s_ashr_i32 s21, s20, 31
	s_lshl_b64 s[20:21], s[20:21], 19
	s_add_u32 s20, s4, s20
	s_addc_u32 s21, s5, s21
	s_ashr_i32 s23, s22, 31
	s_lshl_b64 s[22:23], s[22:23], 19
	s_add_u32 s22, s31, s22
	s_addc_u32 s23, s33, s23

; __device__ __forceinline__ bool tile_of(long Lidx, int nM, int nN, int& pm, int& pn) {
;     const int nwg = nM * nN; if (Lidx >= nwg) return false;
;     int wgid = (int)Lidx; { const int q = nwg / NXCD, r = nwg % NXCD, xcd = wgid % NXCD, off = wgid / NXCD; wgid = (xcd < r ? xcd * (q + 1) : r * (q + 1) + (xcd - r) * q) + off; }
; template <class Epi, class Sched>
; __device__ __forceinline__ void gemm_phase(LAS unsigned char* lds, const Sched& S, const Epi& E) {
;     ...
;         { int efr = fr, efq = fq, eui = ui; asm volatile("" : "+v"(efr), "+v"(efq), "+s"(eui));
;           Unit eu; S.next(eui, eu); keep = E(acc, eu, wr, wc, efr, efq); }
.LBB0_1195:
	v_mov_b32_e32 v132, v136
	v_mov_b32_e32 v133, v137
	v_mov_b32_e32 v143, s28
	v_mov_b64_e32 v[144:145], s[2:3]
	s_nop 0
	v_mad_i64_i32 v[144:145], s[24:25], s19, v143, v[144:145]
	v_cmp_lt_i64_e32 vcc, s[16:17], v[144:145]
	v_readfirstlane_b32 s19, v144
	s_cbranch_vccnz .LBB0_1201
	s_cmp_lt_i32 s101, 0
	s_cbranch_scc1 .Lcalc_full_4
	s_mov_b32 s18, s100
	s_mov_b32 s57, s101
	s_branch .LBB0_1201
.Lcalc_full_4:
	s_ashr_i32 s18, s19, 31
	s_lshr_b32 s18, s18, 29
	s_add_i32 s24, s19, s18
	s_and_b32 s18, s24, -8
	s_sub_i32 s25, s19, s18
	s_cmp_gt_i32 s25, -1
	s_mov_b64 s[18:19], -1
	s_cbranch_scc0 .LBB0_1198
	s_lshl_b32 s26, s25, 6
	s_mov_b64 s[18:19], 0

; #define PG8_STAGE(bufoff, gbase, voff, p64) do { _Pragma("unroll") for (int _i = 0; _i < 2; ++_i) { \
;         const char* _gb = (const char*)(gbase) + (size_t)_i * (p64); const unsigned _la = ldsbase + (unsigned)(bufoff) + (unsigned)_i * 8192u; \
;         asm volatile("s_mov_b32 m0, %0\n\ts_nop 0\n\tglobal_load_lds_dwordx4 %1, %2" :: "s"(_la), "v"(voff), "s"(_gb) : "memory"); } } while (0)
; #define PG8_WAIT_V(n) asm volatile("s_waitcnt vmcnt(" #n ")" ::: "memory")
; #define PG8_BAR __builtin_amdgcn_s_barrier()
; template <class Epi, class Sched>
; __device__ __forceinline__ void gemm_phase(LAS unsigned char* lds, const Sched& S, const Epi& E) {
;     ...
;     PG8_STAGE(PG8_SB(0, 0), cB, voffB, hB / 2); PG8_STAGE(PG8_SB(0, 1), cB + hB, voffB, hB / 2); PG8_STAGE(PG8_SA(0, 0), cA, voffA, hA / 2); PG8_STAGE(PG8_SA(0, 1), cA + hA, voffA, hA / 2);
;     if (wr == 1) PG8_BAR;
;     PG8_WAIT_V(2); PG8_BAR;
;     PG8_STAGE(PG8_SB(1, 0), cB + kstep, voffB, hB / 2); PG8_STAGE(PG8_SA(1, 0), cA + kstep, voffA, hA / 2); PG8_STAGE(PG8_SB(1, 1), cB + hB + kstep, voffB, hB / 2);
;     PG8_WAIT_V(6); PG8_BAR;
.LBB0_1264:
	s_add_u32 s12, s8, 0x10900000
	s_addc_u32 s13, s9, 0
	s_add_u32 s14, s8, 0x8900000
	s_addc_u32 s15, s9, 0
	v_bfe_u32 v155, v0, 4, 2
	s_lshl_b32 s6, s6, 5
	v_and_b32_e32 v154, 15, v0
	s_lshl_b32 s50, s16, 6
	v_lshlrev_b32_e32 v1, 4, v155
	s_lshl_b32 s8, s16, 13
	v_lshlrev_b32_e32 v0, 2, v0
	s_and_b32 s16, s6, 0x60
	v_lshl_or_b32 v1, v154, 6, v1
	v_and_b32_e32 v0, 32, v0
	s_lshl_b32 s6, s16, 7
	v_bitop3_b32 v2, v1, s8, v0 bitop3:0xde
	s_add_u32 s8, s40, 0x80
	s_addc_u32 s9, s41, 0
	s_add_i32 s51, s34, 0x18000
	s_waitcnt vmcnt(2)
	s_barrier
	s_mov_b32 m0, s51
	s_nop 0
	global_load_lds_dwordx4 v153, s[8:9]
	s_add_u32 s8, s40, 0x20080
	s_addc_u32 s9, s41, 0
	s_add_i32 s52, s34, 0x1a000
	s_mov_b32 m0, s52
	s_nop 0
	global_load_lds_dwordx4 v153, s[8:9]
	s_add_u32 s8, s38, 0x80
	s_addc_u32 s9, s39, 0
	s_add_i32 s53, s34, 0x8000
	s_mov_b32 m0, s53
	s_nop 0
	global_load_lds_dwordx4 v152, s[8:9]
	s_add_u32 s8, s38, 0x20080
	s_addc_u32 s9, s39, 0
	s_add_i32 s54, s34, 0xa000
	s_mov_b32 m0, s54
	s_nop 0
	global_load_lds_dwordx4 v152, s[8:9]
	s_add_u32 s8, s40, 0x40080
	s_addc_u32 s9, s41, 0
	s_add_i32 s55, s34, 0x1c000
	s_mov_b32 m0, s55
	s_nop 0
	global_load_lds_dwordx4 v153, s[8:9]
	s_add_u32 s8, s40, 0x60080
	s_addc_u32 s9, s41, 0
	s_add_i32 s56, s34, 0x1e000
	s_mov_b32 m0, s56
	s_nop 0
	global_load_lds_dwordx4 v153, s[8:9]
	v_bitop3_b32 v0, v1, s6, v0 bitop3:0xde
	s_waitcnt vmcnt(6)
	s_add_i32 s57, s34, 0xc000
	s_cmpk_lt_u32 s17, 0x100
	v_add_u32_e32 v0, 0, v0
	s_cselect_b64 s[18:19], -1, 0
	s_mov_b32 s17, s7
	s_add_i32 s58, s34, 0xe000
	v_mov_b64_e32 v[136:137], 0x400
	s_mov_b64 s[20:21], 0x3ff
	v_mov_b64_e32 v[138:139], 0x3ff
	v_add_u32_e32 v156, 0x10000, v0
	v_add_u32_e32 v157, 0x14000, v0
	v_add_u32_e32 v158, 0, v2
	v_add_u32_e32 v159, 0x18000, v0
	v_add_u32_e32 v160, 0x1c000, v0
	s_lshl_b32 s6, s16, 1
	s_mov_b32 s23, s7
	s_mov_b64 s[26:27], s[40:41]
	s_mov_b64 s[24:25], s[38:39]
	s_barrier
	s_mov_b32 s99, -1
	s_branch .LBB0_1267

; __device__ __forceinline__ bool tile_of(long Lidx, int nM, int nN, int& pm, int& pn) {
;     const int nwg = nM * nN; if (Lidx >= nwg) return false;
;     int wgid = (int)Lidx; { const int q = nwg / NXCD, r = nwg % NXCD, xcd = wgid % NXCD, off = wgid / NXCD; wgid = (xcd < r ? xcd * (q + 1) : r * (q + 1) + (xcd - r) * q) + off; }
; template <class Epi, class Sched>
; __device__ __forceinline__ void gemm_phase(LAS unsigned char* lds, const Sched& S, const Epi& E) {
;     ...
;         const char* nA = cA; const char* nB = cB; int nnt = nt; bool has_next;
;         { Unit nx; has_next = S.next(ui + 1, nx);
;           if (has_next) { nA = nx.A; nB = nx.B; nnt = nx.nt; } }
.LBB0_1267:
	s_mov_b32 s100, s98
	s_mov_b32 s101, s99
	s_add_i32 s59, s23, 1
	s_mul_i32 s8, s59, s29
	s_mul_hi_u32 s9, s59, s28
	s_add_i32 s9, s9, s8
	s_mul_i32 s8, s59, s28
	s_add_u32 s42, s8, s2
	s_addc_u32 s43, s9, s3
	v_cmp_gt_i64_e32 vcc, s[42:43], v[138:139]
	v_cmp_lt_i64_e64 s[8:9], s[42:43], v[136:137]
	s_cbranch_vccnz .LBB0_1273
	s_ashr_i32 s24, s42, 31
	s_lshr_b32 s24, s24, 29
	s_add_i32 s26, s42, s24
	s_and_b32 s24, s26, -8
	s_sub_i32 s27, s42, s24
	s_cmp_gt_i32 s27, -1
	s_mov_b64 s[24:25], -1
	s_cbranch_scc0 .LBB0_1270
	s_lshl_b32 s42, s27, 7
	s_mov_b64 s[24:25], 0

; __device__ __forceinline__ bool tile_of(long Lidx, int nM, int nN, int& pm, int& pn) {
;     ...
;     const int nig = WGM * nN, gid = wgid / nig, fm = gid * WGM, gsz = (nM - fm) < WGM ? (nM - fm) : WGM;
;     pm = fm + ((wgid % nig) % gsz); pn = (wgid % nig) / gsz; return true;
;     __device__ __forceinline__ bool next(int i, Unit& u) const {
;     ...
;         u.A = A + (size_t)pm * 256 * lda2; u.B = B + (size_t)pn * 256 * ldb2; u.lda2 = lda2; u.ldb2 = ldb2; u.nt = nt; u.kind = 0; u.pm = pm; u.pn = pn; u.z = 0; u.w = 0; return true;
.LBB0_1272:
	s_ashr_i32 s24, s26, 3
	s_add_i32 s24, s42, s24
	s_ashr_i32 s25, s24, 31
	s_lshr_b32 s25, s25, 26
	s_add_i32 s25, s24, s25
	s_ashr_i32 s26, s25, 6
	s_lshl_b32 s27, s26, 3
	s_sub_i32 s26, 0x80, s27
	s_min_i32 s30, s26, 8
	s_andn2_b32 s25, s25, 63
	s_sub_i32 s24, s24, s25
	s_ashr_i32 s26, s24, 3
	s_mul_i32 s25, s26, s30
	s_sub_i32 s24, s24, s25
	s_add_i32 s24, s27, s24
	s_mov_b32 s98, s24
	s_mov_b32 s99, s26
	s_ashr_i32 s25, s24, 31
	s_lshl_b64 s[24:25], s[24:25], 19
	s_add_u32 s24, s4, s24
	s_addc_u32 s25, s5, s25
	s_ashr_i32 s27, s26, 31
	s_lshl_b64 s[26:27], s[26:27], 19
	s_add_u32 s26, s31, s26
	s_addc_u32 s27, s33, s27

; __device__ __forceinline__ bool tile_of(long Lidx, int nM, int nN, int& pm, int& pn) {
;     const int nwg = nM * nN; if (Lidx >= nwg) return false;
;     int wgid = (int)Lidx; { const int q = nwg / NXCD, r = nwg % NXCD, xcd = wgid % NXCD, off = wgid / NXCD; wgid = (xcd < r ? xcd * (q + 1) : r * (q + 1) + (xcd - r) * q) + off; }
; template <class Epi, class Sched>
; __device__ __forceinline__ void gemm_phase(LAS unsigned char* lds, const Sched& S, const Epi& E) {
;     ...
;         { int efr = fr, efq = fq, eui = ui; asm volatile("" : "+v"(efr), "+v"(efq), "+s"(eui));
;           Unit eu; S.next(eui, eu); keep = E(acc, eu, wr, wc, efr, efq); }
.LBB0_1277:
	v_mov_b32_e32 v128, v155
	v_mov_b32_e32 v129, v154
	v_mov_b32_e32 v132, s28
	v_mov_b64_e32 v[130:131], s[2:3]
	s_nop 0
	v_mad_i64_i32 v[130:131], s[38:39], s23, v132, v[130:131]
	v_cmp_lt_i64_e32 vcc, s[20:21], v[130:131]
	v_readfirstlane_b32 s23, v130
	s_cbranch_vccnz .LBB0_1283
	s_cmp_lt_i32 s101, 0
	s_cbranch_scc1 .Lcalc_full_5
	s_mov_b32 s22, s100
	s_mov_b32 s60, s101
	s_branch .LBB0_1283
.Lcalc_full_5:
	s_ashr_i32 s22, s23, 31
	s_lshr_b32 s22, s22, 29
	s_add_i32 s38, s23, s22
	s_and_b32 s22, s38, -8
	s_sub_i32 s39, s23, s22
	s_cmp_gt_i32 s39, -1
	s_mov_b64 s[22:23], -1
	s_cbranch_scc0 .LBB0_1280
	s_lshl_b32 s40, s39, 7
	s_mov_b64 s[22:23], 0

; #define PG8_STAGE(bufoff, gbase, voff, p64) do { _Pragma("unroll") for (int _i = 0; _i < 2; ++_i) { \
;         const char* _gb = (const char*)(gbase) + (size_t)_i * (p64); const unsigned _la = ldsbase + (unsigned)(bufoff) + (unsigned)_i * 8192u; \
;         asm volatile("s_mov_b32 m0, %0\n\ts_nop 0\n\tglobal_load_lds_dwordx4 %1, %2" :: "s"(_la), "v"(voff), "s"(_gb) : "memory"); } } while (0)
; #define PG8_WAIT_V(n) asm volatile("s_waitcnt vmcnt(" #n ")" ::: "memory")
; #define PG8_BAR __builtin_amdgcn_s_barrier()
; template <class Epi, class Sched>
; __device__ __forceinline__ void gemm_phase(LAS unsigned char* lds, const Sched& S, const Epi& E) {
;     ...
;     PG8_STAGE(PG8_SB(0, 0), cB, voffB, hB / 2); PG8_STAGE(PG8_SB(0, 1), cB + hB, voffB, hB / 2); PG8_STAGE(PG8_SA(0, 0), cA, voffA, hA / 2); PG8_STAGE(PG8_SA(0, 1), cA + hA, voffA, hA / 2);
;     if (wr == 1) PG8_BAR;
;     PG8_WAIT_V(2); PG8_BAR;
;     PG8_STAGE(PG8_SB(1, 0), cB + kstep, voffB, hB / 2); PG8_STAGE(PG8_SA(1, 0), cA + kstep, voffA, hA / 2); PG8_STAGE(PG8_SB(1, 1), cB + hB + kstep, voffB, hB / 2);
;     PG8_WAIT_V(6); PG8_BAR;
.LBB0_1342:
	s_add_u32 s44, s6, 0x18900000
	s_addc_u32 s45, s7, 0
	v_bfe_u32 v173, v0, 4, 2
	s_lshl_b32 s9, s9, 5
	v_and_b32_e32 v172, 15, v0
	v_lshlrev_b32_e32 v1, 4, v173
	v_lshlrev_b32_e32 v0, 2, v0
	s_and_b32 s47, s9, 0x60
	s_lshl_b32 s46, s12, 6
	v_lshl_or_b32 v1, v172, 6, v1
	s_lshl_b32 s12, s12, 13
	v_and_b32_e32 v0, 32, v0
	s_lshl_b32 s9, s47, 7
	v_bitop3_b32 v2, v1, s12, v0 bitop3:0xde
	s_add_u32 s12, s24, 0x80
	s_addc_u32 s13, s25, 0
	s_add_i32 s48, s34, 0x18000
	s_waitcnt vmcnt(2)
	s_barrier
	s_mov_b32 m0, s48
	s_nop 0
	global_load_lds_dwordx4 v171, s[12:13]
	s_add_u32 s12, s24, 0x20080
	s_addc_u32 s13, s25, 0
	s_add_i32 s49, s34, 0x1a000
	s_mov_b32 m0, s49
	s_nop 0
	global_load_lds_dwordx4 v171, s[12:13]
	s_add_u32 s12, s22, 0x80
	s_addc_u32 s13, s23, 0
	s_add_i32 s50, s34, 0x8000
	s_mov_b32 m0, s50
	s_nop 0
	global_load_lds_dwordx4 v170, s[12:13]
	s_add_u32 s12, s22, 0x20080
	s_addc_u32 s13, s23, 0
	s_add_i32 s51, s34, 0xa000
	s_mov_b32 m0, s51
	s_nop 0
	global_load_lds_dwordx4 v170, s[12:13]
	s_add_u32 s12, s24, 0x40080
	s_addc_u32 s13, s25, 0
	s_add_i32 s52, s34, 0x1c000
	s_mov_b32 m0, s52
	s_nop 0
	global_load_lds_dwordx4 v171, s[12:13]
	s_add_u32 s12, s24, 0x60080
	s_addc_u32 s13, s25, 0
	s_add_i32 s53, s34, 0x1e000
	s_mov_b32 m0, s53
	s_nop 0
	global_load_lds_dwordx4 v171, s[12:13]
	v_bitop3_b32 v0, v1, s9, v0 bitop3:0xde
	s_waitcnt vmcnt(6)
	s_add_i32 s54, s34, 0xc000
	s_cmpk_lt_u32 s8, 0x100
	v_add_u32_e32 v0, 0, v0
	s_cselect_b64 s[12:13], -1, 0
	s_add_i32 s55, s34, 0xe000
	v_mov_b64_e32 v[140:141], 0x200
	s_mov_b64 s[14:15], 0x1ff
	v_mov_b64_e32 v[142:143], 0x1ff
	v_add_u32_e32 v174, 0x10000, v0
	v_add_u32_e32 v175, 0x14000, v0
	v_add_u32_e32 v177, 0, v2
	v_add_u32_e32 v178, 0x18000, v0
	v_add_u32_e32 v179, 0x1c000, v0
	s_movk_i32 s56, 0x2400
	s_mov_b64 s[20:21], s[24:25]
	s_mov_b64 s[18:19], s[22:23]
	s_barrier
	s_mov_b32 s99, -1
	s_branch .LBB0_1345

; __device__ __forceinline__ bool tile_of(long Lidx, int nM, int nN, int& pm, int& pn) {
;     const int nwg = nM * nN; if (Lidx >= nwg) return false;
;     int wgid = (int)Lidx; { const int q = nwg / NXCD, r = nwg % NXCD, xcd = wgid % NXCD, off = wgid / NXCD; wgid = (xcd < r ? xcd * (q + 1) : r * (q + 1) + (xcd - r) * q) + off; }
; template <class Epi, class Sched>
; __device__ __forceinline__ void gemm_phase(LAS unsigned char* lds, const Sched& S, const Epi& E) {
;     ...
;         const char* nA = cA; const char* nB = cB; int nnt = nt; bool has_next;
;         { Unit nx; has_next = S.next(ui + 1, nx);
;           if (has_next) { nA = nx.A; nB = nx.B; nnt = nx.nt; } }
.LBB0_1345:
	s_mov_b32 s100, s98
	s_mov_b32 s101, s99
	s_add_i32 s57, s17, 1
	s_mul_i32 s8, s57, s29
	s_mul_hi_u32 s9, s57, s28
	s_add_i32 s9, s9, s8
	s_mul_i32 s8, s57, s28
	s_add_u32 s26, s8, s2
	s_addc_u32 s27, s9, s3
	v_cmp_gt_i64_e32 vcc, s[26:27], v[142:143]
	v_cmp_lt_i64_e64 s[8:9], s[26:27], v[140:141]
	s_cbranch_vccnz .LBB0_1351
	s_ashr_i32 s18, s26, 31
	s_lshr_b32 s18, s18, 29
	s_add_i32 s20, s26, s18
	s_and_b32 s18, s20, -8
	s_sub_i32 s21, s26, s18
	s_cmp_gt_i32 s21, -1
	s_mov_b64 s[18:19], -1
	s_cbranch_scc0 .LBB0_1348
	s_lshl_b32 s26, s21, 6
	s_mov_b64 s[18:19], 0

; __device__ __forceinline__ bool tile_of(long Lidx, int nM, int nN, int& pm, int& pn) {
;     ...
;     const int nig = WGM * nN, gid = wgid / nig, fm = gid * WGM, gsz = (nM - fm) < WGM ? (nM - fm) : WGM;
;     pm = fm + ((wgid % nig) % gsz); pn = (wgid % nig) / gsz; return true;
;     __device__ __forceinline__ bool next(int i, Unit& u) const {
;     ...
;         u.A = A + (size_t)pm * 256 * lda2; u.B = B + (size_t)pn * 256 * ldb2; u.lda2 = lda2; u.ldb2 = ldb2; u.nt = nt; u.kind = 0; u.pm = pm; u.pn = pn; u.z = 0; u.w = 0; return true;
.LBB0_1350:
	s_ashr_i32 s18, s20, 3
	s_add_i32 s18, s26, s18
	s_ashr_i32 s19, s18, 31
	s_lshr_b32 s19, s19, 27
	s_add_i32 s19, s18, s19
	s_ashr_i32 s20, s19, 5
	s_lshl_b32 s21, s20, 3
	s_sub_i32 s20, 0x80, s21
	s_min_i32 s26, s20, 8
	s_andn2_b32 s19, s19, 31
	s_sub_i32 s18, s18, s19
	s_ashr_i32 s20, s18, 3
	s_mul_i32 s19, s20, s26
	s_sub_i32 s18, s18, s19
	s_add_i32 s18, s21, s18
	s_mov_b32 s98, s18
	s_mov_b32 s99, s20
	s_ashr_i32 s19, s18, 31
	s_lshl_b64 s[18:19], s[18:19], 19
	s_add_u32 s18, s4, s18
	s_addc_u32 s19, s5, s19
	s_ashr_i32 s21, s20, 31
	s_lshl_b64 s[20:21], s[20:21], 19
	s_add_u32 s20, s31, s20
	s_addc_u32 s21, s33, s21

; __device__ __forceinline__ bool tile_of(long Lidx, int nM, int nN, int& pm, int& pn) {
;     const int nwg = nM * nN; if (Lidx >= nwg) return false;
;     int wgid = (int)Lidx; { const int q = nwg / NXCD, r = nwg % NXCD, xcd = wgid % NXCD, off = wgid / NXCD; wgid = (xcd < r ? xcd * (q + 1) : r * (q + 1) + (xcd - r) * q) + off; }
; template <class Epi, class Sched>
; __device__ __forceinline__ void gemm_phase(LAS unsigned char* lds, const Sched& S, const Epi& E) {
;     ...
;         { int efr = fr, efq = fq, eui = ui; asm volatile("" : "+v"(efr), "+v"(efq), "+s"(eui));
;           Unit eu; S.next(eui, eu); keep = E(acc, eu, wr, wc, efr, efq); }
.LBB0_1355:
	v_mov_b32_e32 v129, v172
	v_mov_b32_e32 v128, v173
	v_mov_b32_e32 v132, s28
	v_mov_b64_e32 v[130:131], s[2:3]
	s_nop 0
	v_mad_i64_i32 v[130:131], s[22:23], s17, v132, v[130:131]
	v_cmp_lt_i64_e32 vcc, s[14:15], v[130:131]
	v_readfirstlane_b32 s17, v130
	s_cbranch_vccnz .LBB0_1361
	s_cmp_lt_i32 s101, 0
	s_cbranch_scc1 .Lcalc_full_6
	s_mov_b32 s16, s100
	s_mov_b32 s58, s101
	s_branch .LBB0_1361
.Lcalc_full_6:
	s_ashr_i32 s16, s17, 31
	s_lshr_b32 s16, s16, 29
	s_add_i32 s22, s17, s16
	s_and_b32 s16, s22, -8
	s_sub_i32 s23, s17, s16
	s_cmp_gt_i32 s23, -1
	s_mov_b64 s[16:17], -1
	s_cbranch_scc0 .LBB0_1358
	s_lshl_b32 s24, s23, 6
	s_mov_b64 s[16:17], 0

; #define PG8_STAGE(bufoff, gbase, voff, p64) do { _Pragma("unroll") for (int _i = 0; _i < 2; ++_i) { \
;         const char* _gb = (const char*)(gbase) + (size_t)_i * (p64); const unsigned _la = ldsbase + (unsigned)(bufoff) + (unsigned)_i * 8192u; \
;         asm volatile("s_mov_b32 m0, %0\n\ts_nop 0\n\tglobal_load_lds_dwordx4 %1, %2" :: "s"(_la), "v"(voff), "s"(_gb) : "memory"); } } while (0)
; #define PG8_WAIT_V(n) asm volatile("s_waitcnt vmcnt(" #n ")" ::: "memory")
; #define PG8_BAR __builtin_amdgcn_s_barrier()
; template <class Epi, class Sched>
; __device__ __forceinline__ void gemm_phase(LAS unsigned char* lds, const Sched& S, const Epi& E) {
;     ...
;     PG8_STAGE(PG8_SB(0, 0), cB, voffB, hB / 2); PG8_STAGE(PG8_SB(0, 1), cB + hB, voffB, hB / 2); PG8_STAGE(PG8_SA(0, 0), cA, voffA, hA / 2); PG8_STAGE(PG8_SA(0, 1), cA + hA, voffA, hA / 2);
;     if (wr == 1) PG8_BAR;
;     PG8_WAIT_V(2); PG8_BAR;
;     PG8_STAGE(PG8_SB(1, 0), cB + kstep, voffB, hB / 2); PG8_STAGE(PG8_SA(1, 0), cA + kstep, voffA, hA / 2); PG8_STAGE(PG8_SB(1, 1), cB + hB + kstep, voffB, hB / 2);
;     PG8_WAIT_V(6); PG8_BAR;
.LBB0_1479:
	s_add_u32 s12, s8, 0x8900000
	v_bfe_u32 v137, v0, 4, 2
	s_addc_u32 s13, s9, 0
	v_and_b32_e32 v136, 15, v0
	v_lshlrev_b32_e32 v1, 4, v137
	v_lshlrev_b32_e32 v0, 2, v0
	s_lshl_b32 s6, s6, 5
	v_lshl_or_b32 v1, v136, 6, v1
	s_lshl_b32 s8, s15, 13
	v_and_b32_e32 v0, 32, v0
	s_and_b32 s6, s6, 0x60
	s_lshl_b32 s47, s15, 6
	v_bitop3_b32 v2, v1, s8, v0 bitop3:0xde
	s_lshl_b32 s8, s6, 7
	v_bitop3_b32 v0, v1, s8, v0 bitop3:0xde
	s_add_u32 s8, s26, 0x80
	s_addc_u32 s9, s27, 0
	s_add_i32 s48, s34, 0x18000
	s_waitcnt vmcnt(2)
	s_barrier
	s_mov_b32 m0, s48
	s_nop 0
	global_load_lds_dwordx4 v135, s[8:9]
	s_add_u32 s8, s26, 0x20080
	s_addc_u32 s9, s27, 0
	s_add_i32 s49, s34, 0x1a000
	s_mov_b32 m0, s49
	s_nop 0
	global_load_lds_dwordx4 v135, s[8:9]
	s_add_u32 s8, s24, 0x80
	s_addc_u32 s9, s25, 0
	s_add_i32 s50, s34, 0x8000
	s_mov_b32 m0, s50
	s_nop 0
	global_load_lds_dwordx4 v134, s[8:9]
	s_add_u32 s8, s24, 0x20080
	s_addc_u32 s9, s25, 0
	s_add_i32 s51, s34, 0xa000
	s_mov_b32 m0, s51
	s_nop 0
	global_load_lds_dwordx4 v134, s[8:9]
	s_add_u32 s8, s26, 0x40080
	s_addc_u32 s9, s27, 0
	s_add_i32 s52, s34, 0x1c000
	s_mov_b32 m0, s52
	s_nop 0
	global_load_lds_dwordx4 v135, s[8:9]
	s_add_u32 s8, s26, 0x60080
	s_addc_u32 s9, s27, 0
	s_add_i32 s53, s34, 0x1e000
	s_mov_b32 m0, s53
	s_nop 0
	global_load_lds_dwordx4 v135, s[8:9]
	s_waitcnt vmcnt(6)
	s_add_i32 s54, s34, 0xc000
	s_cmpk_lt_u32 s14, 0x100
	v_add_u32_e32 v0, 0, v0
	s_cselect_b64 s[14:15], -1, 0
	s_add_i32 s55, s34, 0xe000
	v_mov_b64_e32 v[128:129], 0xb00
	s_mov_b64 s[16:17], 0xaff
	v_mov_b64_e32 v[130:131], 0xaff
	v_add_u32_e32 v138, 0x10000, v0
	v_add_u32_e32 v139, 0x14000, v0
	v_add_u32_e32 v140, 0, v2
	v_add_u32_e32 v141, 0x18000, v0
	v_add_u32_e32 v142, 0x1c000, v0
	s_movk_i32 s56, 0x1600
	s_lshl_b32 s6, s6, 1
	s_mov_b32 s19, s7
	s_mov_b64 s[20:21], s[24:25]
	s_mov_b64 s[22:23], s[26:27]
	s_barrier
	s_waitcnt vmcnt(0)
	s_mov_b32 s99, -1
	s_branch .LBB0_1482

; __device__ __forceinline__ bool tile_of(long Lidx, int nM, int nN, int& pm, int& pn) {
;     const int nwg = nM * nN; if (Lidx >= nwg) return false;
;     int wgid = (int)Lidx; { const int q = nwg / NXCD, r = nwg % NXCD, xcd = wgid % NXCD, off = wgid / NXCD; wgid = (xcd < r ? xcd * (q + 1) : r * (q + 1) + (xcd - r) * q) + off; }
;     const int nig = WGM * nN, gid = wgid / nig, fm = gid * WGM, gsz = (nM - fm) < WGM ? (nM - fm) : WGM;
;     pm = fm + ((wgid % nig) % gsz); pn = (wgid % nig) / gsz; return true;
; template <class Epi, class Sched>
; __device__ __forceinline__ void gemm_phase(LAS unsigned char* lds, const Sched& S, const Epi& E) {
;     ...
;         const char* nA = cA; const char* nB = cB; int nnt = nt; bool has_next;
;         { Unit nx; has_next = S.next(ui + 1, nx);
;           if (has_next) { nA = nx.A; nB = nx.B; nnt = nx.nt; } }
.LBB0_1482:
	s_mov_b32 s100, s98
	s_mov_b32 s101, s99
	s_add_i32 s57, s19, 1
	s_mul_i32 s8, s57, s29
	s_mul_hi_u32 s9, s57, s28
	s_add_i32 s9, s9, s8
	s_mul_i32 s8, s57, s28
	s_add_u32 s38, s8, s2
	s_addc_u32 s39, s9, s3
	v_cmp_gt_i64_e32 vcc, s[38:39], v[130:131]
	v_cmp_lt_i64_e64 s[8:9], s[38:39], v[128:129]
	s_cbranch_vccnz .LBB0_1484
	s_ashr_i32 s20, s38, 31
	s_lshr_b32 s20, s20, 29
	s_add_i32 s20, s38, s20
	s_ashr_i32 s21, s20, 3
	s_and_b32 s20, s20, -8
	s_sub_i32 s20, s38, s20
	s_cmp_lt_i32 s20, 0
	s_cselect_b32 s22, s35, 0x160
	s_mul_i32 s20, s20, s22
	s_add_i32 s20, s20, s21
	s_mul_hi_i32 s21, s20, 0x2e8ba2e9
	s_lshr_b32 s22, s21, 31
	s_ashr_i32 s21, s21, 5
	s_add_i32 s21, s21, s22
	s_lshl_b32 s23, s21, 3
	s_sub_i32 s22, 0x80, s23
	s_min_i32 s30, s22, 8
	s_mulk_i32 s21, 0xb0
	s_sub_i32 s20, s20, s21
	s_ashr_i32 s22, s20, 3
	s_mul_i32 s21, s22, s30
	s_sub_i32 s20, s20, s21
	s_add_i32 s20, s23, s20
	s_mov_b32 s98, s20
	s_mov_b32 s99, s22
	s_ashr_i32 s21, s20, 31
	s_lshl_b64 s[20:21], s[20:21], 19
	s_add_u32 s20, s4, s20
	s_addc_u32 s21, s5, s21
	s_ashr_i32 s23, s22, 31
	s_lshl_b64 s[22:23], s[22:23], 19
	s_add_u32 s22, s31, s22
	s_addc_u32 s23, s33, s23

; __device__ __forceinline__ bool tile_of(long Lidx, int nM, int nN, int& pm, int& pn) {
;     const int nwg = nM * nN; if (Lidx >= nwg) return false;
;     int wgid = (int)Lidx; { const int q = nwg / NXCD, r = nwg % NXCD, xcd = wgid % NXCD, off = wgid / NXCD; wgid = (xcd < r ? xcd * (q + 1) : r * (q + 1) + (xcd - r) * q) + off; }
; template <class Epi, class Sched>
; __device__ __forceinline__ void gemm_phase(LAS unsigned char* lds, const Sched& S, const Epi& E) {
;     ...
;         { int efr = fr, efq = fq, eui = ui; asm volatile("" : "+v"(efr), "+v"(efq), "+s"(eui));
;           Unit eu; S.next(eui, eu); keep = E(acc, eu, wr, wc, efr, efq); }
.LBB0_1488:
	v_mov_b32_e32 v133, v137
	v_mov_b32_e32 v132, v136
	v_mov_b32_e32 v143, s28
	v_mov_b64_e32 v[144:145], s[2:3]
	s_nop 0
	v_mad_i64_i32 v[144:145], s[24:25], s19, v143, v[144:145]
	v_cmp_lt_i64_e32 vcc, s[16:17], v[144:145]
	v_readfirstlane_b32 s19, v144
	s_cbranch_vccnz .LBB0_1490
	s_cmp_lt_i32 s101, 0
	s_cbranch_scc1 .Lcalc_full_7
	s_mov_b32 s18, s100
	s_mov_b32 s58, s101
	s_branch .LBB0_1490
.Lcalc_full_7:
	s_ashr_i32 s18, s19, 31
	s_lshr_b32 s18, s18, 29
	s_add_i32 s18, s19, s18
	s_ashr_i32 s24, s18, 3
	s_and_b32 s18, s18, -8
	s_sub_i32 s18, s19, s18
	s_cmp_lt_i32 s18, 0
	s_cselect_b32 s19, s35, 0x160
	s_mul_i32 s18, s18, s19
	s_add_i32 s18, s18, s24
	s_mul_hi_i32 s19, s18, 0x2e8ba2e9
	s_lshr_b32 s24, s19, 31
	s_ashr_i32 s19, s19, 5
	s_add_i32 s19, s19, s24
	s_lshl_b32 s24, s19, 3
	s_sub_i32 s25, 0x80, s24
	s_min_i32 s25, s25, 8
	s_mulk_i32 s19, 0xb0
	s_sub_i32 s18, s18, s19
	s_ashr_i32 s58, s18, 3
	s_mul_i32 s19, s58, s25
	s_sub_i32 s18, s18, s19
	s_add_i32 s18, s24, s18

; #define PG8_STAGE(bufoff, gbase, voff, p64) do { _Pragma("unroll") for (int _i = 0; _i < 2; ++_i) { \
;         const char* _gb = (const char*)(gbase) + (size_t)_i * (p64); const unsigned _la = ldsbase + (unsigned)(bufoff) + (unsigned)_i * 8192u; \
;         asm volatile("s_mov_b32 m0, %0\n\ts_nop 0\n\tglobal_load_lds_dwordx4 %1, %2" :: "s"(_la), "v"(voff), "s"(_gb) : "memory"); } } while (0)
; #define PG8_WAIT_V(n) asm volatile("s_waitcnt vmcnt(" #n ")" ::: "memory")
; #define PG8_BAR __builtin_amdgcn_s_barrier()
; template <class Epi, class Sched>
; __device__ __forceinline__ void gemm_phase(LAS unsigned char* lds, const Sched& S, const Epi& E) {
;     ...
;     PG8_STAGE(PG8_SB(0, 0), cB, voffB, hB / 2); PG8_STAGE(PG8_SB(0, 1), cB + hB, voffB, hB / 2); PG8_STAGE(PG8_SA(0, 0), cA, voffA, hA / 2); PG8_STAGE(PG8_SA(0, 1), cA + hA, voffA, hA / 2);
;     if (wr == 1) PG8_BAR;
;     PG8_WAIT_V(2); PG8_BAR;
;     PG8_STAGE(PG8_SB(1, 0), cB + kstep, voffB, hB / 2); PG8_STAGE(PG8_SA(1, 0), cA + kstep, voffA, hA / 2); PG8_STAGE(PG8_SB(1, 1), cB + hB + kstep, voffB, hB / 2);
;     PG8_WAIT_V(6); PG8_BAR;
.LBB0_1549:
	s_add_u32 s44, s8, 0x18900000
	s_addc_u32 s45, s9, 0
	v_bfe_u32 v178, v0, 4, 2
	s_lshl_b32 s6, s6, 5
	v_and_b32_e32 v177, 15, v0
	v_lshlrev_b32_e32 v1, 4, v178
	v_lshlrev_b32_e32 v0, 2, v0
	s_and_b32 s47, s6, 0x60
	s_lshl_b32 s46, s7, 6
	v_lshl_or_b32 v1, v177, 6, v1
	s_lshl_b32 s7, s7, 13
	v_and_b32_e32 v0, 32, v0
	s_lshl_b32 s6, s47, 7
	v_bitop3_b32 v2, v1, s7, v0 bitop3:0xde
	v_bitop3_b32 v0, v1, s6, v0 bitop3:0xde
	s_add_u32 s6, s24, 0x80
	s_addc_u32 s7, s25, 0
	s_add_i32 s48, s34, 0x18000
	s_waitcnt vmcnt(2)
	s_barrier
	s_mov_b32 m0, s48
	s_nop 0
	global_load_lds_dwordx4 v145, s[6:7]
	s_add_u32 s6, s24, 0x58080
	s_addc_u32 s7, s25, 0
	s_add_i32 s49, s34, 0x1a000
	s_mov_b32 m0, s49
	s_nop 0
	global_load_lds_dwordx4 v145, s[6:7]
	s_add_u32 s6, s22, 0x80
	s_addc_u32 s7, s23, 0
	s_add_i32 s50, s34, 0x8000
	s_mov_b32 m0, s50
	s_nop 0
	global_load_lds_dwordx4 v144, s[6:7]
	s_add_u32 s6, s22, 0x58080
	s_addc_u32 s7, s23, 0
	s_add_i32 s51, s34, 0xa000
	s_mov_b32 m0, s51
	s_nop 0
	global_load_lds_dwordx4 v144, s[6:7]
	s_add_u32 s6, s24, 0xb0080
	s_addc_u32 s7, s25, 0
	s_add_i32 s52, s34, 0x1c000
	s_mov_b32 m0, s52
	s_nop 0
	global_load_lds_dwordx4 v145, s[6:7]
	s_add_u32 s6, s24, 0x108080
	s_addc_u32 s7, s25, 0
	s_add_i32 s53, s34, 0x1e000
	s_mov_b32 m0, s53
	s_nop 0
	global_load_lds_dwordx4 v145, s[6:7]
	s_waitcnt vmcnt(6)
	s_add_i32 s54, s34, 0xc000
	s_cmpk_lt_u32 s12, 0x100
	v_add_u32_e32 v0, 0, v0
	s_cselect_b64 s[12:13], -1, 0
	s_add_i32 s55, s34, 0xe000
	v_mov_b64_e32 v[146:147], 0x200
	s_mov_b64 s[14:15], 0x1ff
	v_mov_b64_e32 v[148:149], 0x1ff
	v_add_u32_e32 v179, 0x10000, v0
	v_add_u32_e32 v180, 0x14000, v0
	v_add_u32_e32 v181, 0, v2
	v_add_u32_e32 v182, 0x18000, v0
	v_add_u32_e32 v183, 0x1c000, v0
	s_movk_i32 s56, 0x2400
	s_mov_b64 s[20:21], s[24:25]
	s_mov_b64 s[18:19], s[22:23]
	s_barrier
	s_mov_b32 s99, -1
	s_branch .LBB0_1552

; __device__ __forceinline__ bool tile_of(long Lidx, int nM, int nN, int& pm, int& pn) {
;     const int nwg = nM * nN; if (Lidx >= nwg) return false;
;     int wgid = (int)Lidx; { const int q = nwg / NXCD, r = nwg % NXCD, xcd = wgid % NXCD, off = wgid / NXCD; wgid = (xcd < r ? xcd * (q + 1) : r * (q + 1) + (xcd - r) * q) + off; }
; template <class Epi, class Sched>
; __device__ __forceinline__ void gemm_phase(LAS unsigned char* lds, const Sched& S, const Epi& E) {
;     ...
;         const char* nA = cA; const char* nB = cB; int nnt = nt; bool has_next;
;         { Unit nx; has_next = S.next(ui + 1, nx);
;           if (has_next) { nA = nx.A; nB = nx.B; nnt = nx.nt; } }
.LBB0_1552:
	s_mov_b32 s100, s98
	s_mov_b32 s101, s99
	s_add_i32 s57, s17, 1
	s_mul_i32 s6, s57, s29
	s_mul_hi_u32 s7, s57, s28
	s_add_i32 s7, s7, s6
	s_mul_i32 s6, s57, s28
	s_add_u32 s26, s6, s2
	s_addc_u32 s27, s7, s3
	v_cmp_gt_i64_e32 vcc, s[26:27], v[148:149]
	v_cmp_lt_i64_e64 s[6:7], s[26:27], v[146:147]
	s_cbranch_vccnz .LBB0_1558
	s_ashr_i32 s18, s26, 31
	s_lshr_b32 s18, s18, 29
	s_add_i32 s20, s26, s18
	s_and_b32 s18, s20, -8
	s_sub_i32 s21, s26, s18
	s_cmp_gt_i32 s21, -1
	s_mov_b64 s[18:19], -1
	s_cbranch_scc0 .LBB0_1555
	s_lshl_b32 s26, s21, 6
	s_mov_b64 s[18:19], 0

; __device__ __forceinline__ bool tile_of(long Lidx, int nM, int nN, int& pm, int& pn) {
;     ...
;     const int nig = WGM * nN, gid = wgid / nig, fm = gid * WGM, gsz = (nM - fm) < WGM ? (nM - fm) : WGM;
;     pm = fm + ((wgid % nig) % gsz); pn = (wgid % nig) / gsz; return true;
;     __device__ __forceinline__ bool next(int i, Unit& u) const {
;     ...
;         u.A = A + (size_t)pm * 256 * lda2; u.B = B + (size_t)pn * 256 * ldb2; u.lda2 = lda2; u.ldb2 = ldb2; u.nt = nt; u.kind = 0; u.pm = pm; u.pn = pn; u.z = 0; u.w = 0; return true;
.LBB0_1557:
	s_ashr_i32 s18, s20, 3
	s_add_i32 s18, s26, s18
	s_ashr_i32 s19, s18, 31
	s_lshr_b32 s19, s19, 27
	s_add_i32 s19, s18, s19
	s_ashr_i32 s20, s19, 5
	s_lshl_b32 s20, s20, 3
	s_sub_i32 s21, 0x80, s20
	s_min_i32 s21, s21, 8
	s_andn2_b32 s19, s19, 31
	s_sub_i32 s18, s18, s19
	s_ashr_i32 s26, s18, 3
	s_mul_i32 s19, s26, s21
	s_sub_i32 s18, s18, s19
	s_add_i32 s18, s20, s18
	s_mov_b32 s98, s18
	s_mov_b32 s99, s26
	s_mul_hi_i32 s19, s18, 0x160000
	s_mul_i32 s18, s18, 0x160000
	s_add_u32 s18, s4, s18
	s_addc_u32 s19, s5, s19
	s_mul_hi_i32 s21, s26, 0x160000
	s_mul_i32 s26, s26, 0x160000
	s_add_u32 s20, s31, s26
	s_addc_u32 s21, s33, s21

; __device__ __forceinline__ bool tile_of(long Lidx, int nM, int nN, int& pm, int& pn) {
;     const int nwg = nM * nN; if (Lidx >= nwg) return false;
;     int wgid = (int)Lidx; { const int q = nwg / NXCD, r = nwg % NXCD, xcd = wgid % NXCD, off = wgid / NXCD; wgid = (xcd < r ? xcd * (q + 1) : r * (q + 1) + (xcd - r) * q) + off; }
; template <class Epi, class Sched>
; __device__ __forceinline__ void gemm_phase(LAS unsigned char* lds, const Sched& S, const Epi& E) {
;     ...
;         { int efr = fr, efq = fq, eui = ui; asm volatile("" : "+v"(efr), "+v"(efq), "+s"(eui));
;           Unit eu; S.next(eui, eu); keep = E(acc, eu, wr, wc, efr, efq); }
.LBB0_1562:
	v_mov_b32_e32 v128, v178
	v_mov_b32_e32 v129, v177
	v_mov_b32_e32 v132, s28
	v_mov_b64_e32 v[130:131], s[2:3]
	s_nop 0
	v_mad_i64_i32 v[130:131], s[22:23], s17, v132, v[130:131]
	v_cmp_lt_i64_e32 vcc, s[14:15], v[130:131]
	v_readfirstlane_b32 s17, v130
	s_cbranch_vccnz .LBB0_1568
	s_cmp_lt_i32 s101, 0
	s_cbranch_scc1 .Lcalc_full_8
	s_mov_b32 s16, s100
	s_mov_b32 s58, s101
	s_branch .LBB0_1568

; __global__ void __launch_bounds__(512, 2) fwd_megakernel(Params Parg) {
	.amdhsa_kernel _Z14fwd_megakernel6Params
		.amdhsa_group_segment_fixed_size 0
		.amdhsa_private_segment_fixed_size 0
		.amdhsa_kernarg_size 472
		.amdhsa_user_sgpr_count 2
		.amdhsa_user_sgpr_dispatch_ptr 0
		.amdhsa_user_sgpr_queue_ptr 0
		.amdhsa_user_sgpr_kernarg_segment_ptr 1
		.amdhsa_user_sgpr_dispatch_id 0
		.amdhsa_user_sgpr_kernarg_preload_length 0
		.amdhsa_user_sgpr_kernarg_preload_offset 0
		.amdhsa_user_sgpr_private_segment_size 0
		.amdhsa_uses_dynamic_stack 0
		.amdhsa_enable_private_segment 0
		.amdhsa_system_sgpr_workgroup_id_x 1
		.amdhsa_system_sgpr_workgroup_id_y 0
		.amdhsa_system_sgpr_workgroup_id_z 0
		.amdhsa_system_sgpr_workgroup_info 0
		.amdhsa_system_vgpr_workitem_id 2
		.amdhsa_next_free_vgpr 256
		.amdhsa_next_free_sgpr 102
		.amdhsa_accum_offset 256
		.amdhsa_reserve_vcc 1
		.amdhsa_float_round_mode_32 0
		.amdhsa_float_round_mode_16_64 0
		.amdhsa_float_denorm_mode_32 3
		.amdhsa_float_denorm_mode_16_64 3
		.amdhsa_dx10_clamp 1
		.amdhsa_ieee_mode 1
		.amdhsa_fp16_overflow 0
		.amdhsa_tg_split 0
		.amdhsa_exception_fp_ieee_invalid_op 0
		.amdhsa_exception_fp_denorm_src 0
		.amdhsa_exception_fp_ieee_div_zero 0
		.amdhsa_exception_fp_ieee_overflow 0
		.amdhsa_exception_fp_ieee_underflow 0
		.amdhsa_exception_fp_ieee_inexact 0
		.amdhsa_exception_int_div_zero 0
	.end_amdhsa_kernel

; __global__ void __launch_bounds__(512, 2) fwd_megakernel(Params Parg) {
amdhsa.kernels:
  - .agpr_count:     0
    .args:
      - .offset:         0
        .size:           216
        .value_kind:     by_value
      - .offset:         216
        .size:           4
        .value_kind:     hidden_block_count_x
      - .offset:         220
        .size:           4
        .value_kind:     hidden_block_count_y
      - .offset:         224
        .size:           4
        .value_kind:     hidden_block_count_z
      - .offset:         228
        .size:           2
        .value_kind:     hidden_group_size_x
      - .offset:         230
        .size:           2
        .value_kind:     hidden_group_size_y
      - .offset:         232
        .size:           2
        .value_kind:     hidden_group_size_z
      - .offset:         234
        .size:           2
        .value_kind:     hidden_remainder_x
      - .offset:         236
        .size:           2
        .value_kind:     hidden_remainder_y
      - .offset:         238
        .size:           2
        .value_kind:     hidden_remainder_z
      - .offset:         256
        .size:           8
        .value_kind:     hidden_global_offset_x
      - .offset:         264
        .size:           8
        .value_kind:     hidden_global_offset_y
      - .offset:         272
        .size:           8
        .value_kind:     hidden_global_offset_z
      - .offset:         280
        .size:           2
        .value_kind:     hidden_grid_dims
      - .offset:         304
        .size:           8
        .value_kind:     hidden_multigrid_sync_arg
      - .offset:         336
        .size:           4
        .value_kind:     hidden_dynamic_lds_size
    .group_segment_fixed_size: 0
    .kernarg_segment_align: 8
    .kernarg_segment_size: 472
    .language:       OpenCL C
    .language_version:
      - 2
      - 0
    .max_flat_workgroup_size: 512
    .name:           _Z14fwd_megakernel6Params
    .private_segment_fixed_size: 0
    .sgpr_count:     108
    .sgpr_spill_count: 73
    .symbol:         _Z14fwd_megakernel6Params.kd
    .uniform_work_group_size: 1
    .uses_dynamic_stack: false
    .vgpr_count:     256
    .vgpr_spill_count: 0
    .wavefront_size: 64
